# gather split-tail token processed first (before the 8 main tokens) instead of last
# baseline (speedup 1.0000x reference)
.LBB0_324:
	s_nop 0
	v_readlane_b32 s0, v249, 46
	v_readlane_b32 s1, v249, 47
	s_and_b64 vcc, exec, s[0:1]
	s_cbranch_vccz .LBB0_345
	v_mov_b32_e32 v1, v220
	v_readlane_b32 s0, v249, 0
	s_nop 0
	v_ashrrev_i32_e32 v0, 6, v1
	v_lshl_add_u32 v116, s0, 2, v0
	v_readfirstlane_b32 s60, v0
	v_readlane_b32 s55, v249, 9
	s_mov_b32 s54, 0
	s_movk_i32 s56, 0x4200
	s_mov_b32 s58, 0
	s_mov_b32 s59, 0
	s_movk_i32 s61, 0xe00
	s_cmp_eq_u32 s55, 0x800
	s_cselect_b32 s55, 1, 0
	s_cselect_b32 s56, 0x4000, s56
	s_sub_u32 s57, s56, 1
	s_lshl_b32 s62, s60, 13
	s_or_b32 s62, s62, 0x8000
	v_readlane_b32 s63, v249, 0
	s_add_u32 s2, s63, 0x4000
	s_lshr_b32 s63, s63, 7
	s_and_b32 s63, s63, 2
	s_cmp_eq_u32 s55, 0
	s_cbranch_scc1 .Lg_entry_main
	s_mov_b32 s54, 1
	s_lshl_b32 s58, s60, 8
	s_movk_i32 s61, 0x200
	v_mov_b32_e32 v116, s2
.Lg_entry_main:
	s_movk_i32 s2, 0x4200
	v_cmp_gt_i32_e32 vcc, s2, v116
	s_and_saveexec_b64 s[0:1], vcc
	s_cbranch_execz .LBB0_344
	v_readlane_b32 s2, v249, 37
	v_readlane_b32 s26, v249, 30
	v_readlane_b32 s3, v249, 38
	v_readlane_b32 s27, v249, 31
	s_mul_hi_i32 s4, s2, 0x1400000
	s_mul_i32 s5, s2, 0x1400000
	s_load_dwordx2 s[2:3], s[26:27], 0x160
	v_and_b32_e32 v6, 31, v1
	v_mul_u32_u24_e32 v2, 24, v6
	v_mov_b32_e32 v3, v80
	v_and_b32_e32 v81, 63, v1
	v_and_b32_e32 v255, 32, v81
	v_lshlrev_b32_e32 v255, 2, v255
	s_waitcnt lgkmcnt(0)
	s_add_u32 s2, s2, s5
	s_addc_u32 s3, s3, s4
	v_lshl_add_u64 v[118:119], s[2:3], 0, v[2:3]
	v_lshlrev_b32_e32 v2, 4, v6
	s_getpc_b64 s[4:5]
	s_add_u32 s4, s4, c_cand@rel32@lo+4
	s_addc_u32 s5, s5, c_cand@rel32@hi+12
	v_lshl_add_u64 v[120:121], s[2:3], 0, v[2:3]
	s_load_dwordx4 s[12:15], s[26:27], 0x90
	s_load_dwordx2 s[2:3], s[26:27], 0xc8
	global_load_ubyte v2, v81, s[4:5]
	v_readlane_b32 s16, v249, 13
	s_sub_i32 s10, s16, 19
	s_cmp_lt_u32 s10, 6
	s_cselect_b64 s[4:5], -1, 0
	s_cmp_gt_u32 s10, 5
	v_readlane_b32 s10, v249, 39
	v_readlane_b32 s11, v249, 40
	s_cselect_b64 s[20:21], -1, 0
	s_lshl_b64 s[10:11], s[10:11], 2
	s_waitcnt lgkmcnt(0)
	s_add_u32 s22, s14, s10
	s_addc_u32 s23, s15, s11
	s_add_u32 s24, s12, s10
	s_addc_u32 s25, s13, s11
	s_load_dwordx2 s[10:11], s[26:27], 0x140
	v_lshlrev_b32_e32 v3, 3, v81
	v_lshlrev_b32_e32 v4, 6, v6
	v_mov_b32_e32 v5, v80
	v_lshl_or_b32 v239, v0, 12, v3
	s_waitcnt lgkmcnt(0)
	v_lshl_add_u64 v[122:123], s[10:11], 0, v[4:5]
	v_and_b32_e32 v3, 3, v1
	v_and_b32_e32 v4, 64, v229
	v_cmp_eq_u32_e64 s[12:13], 0, v3
	v_xor_b32_e32 v3, 4, v229
	v_add_u32_e32 v4, 64, v4
	v_cmp_lt_i32_e32 vcc, v3, v4
	v_readlane_b32 s18, v249, 15
	v_readlane_b32 s19, v249, 16
	v_cndmask_b32_e32 v3, v229, v3, vcc
	v_lshlrev_b32_e32 v240, 2, v3
	v_xor_b32_e32 v3, 8, v229
	v_cmp_lt_i32_e32 vcc, v3, v4
	v_readlane_b32 s17, v249, 14
	v_cmp_lt_u32_e64 s[6:7], 31, v81
	v_cndmask_b32_e32 v3, v229, v3, vcc
	v_lshlrev_b32_e32 v241, 2, v3
	v_xor_b32_e32 v3, 16, v229
	v_cmp_lt_i32_e32 vcc, v3, v4
	v_cmp_gt_u32_e64 s[8:9], 32, v81
	v_cmp_gt_u32_e64 s[10:11], 50, v81
	v_cndmask_b32_e32 v3, v229, v3, vcc
	v_lshlrev_b32_e32 v242, 2, v3
	v_xor_b32_e32 v3, 32, v229
	v_cmp_lt_i32_e32 vcc, v3, v4
	s_waitcnt vmcnt(0)
	v_and_b32_e32 v0, 15, v2
	v_cndmask_b32_e32 v3, v229, v3, vcc
	v_lshlrev_b32_e32 v243, 2, v3
	v_and_b32_e32 v3, 16, v1
	v_cmp_eq_u32_e64 s[14:15], 0, v3
	v_and_b32_e32 v3, 8, v1
	v_and_b32_e32 v1, 4, v1
	v_cmp_eq_u32_e64 s[18:19], 0, v1
	v_xor_b32_e32 v1, 2, v229
	v_cmp_lt_i32_e32 vcc, v1, v4
	v_lshrrev_b32_e32 v2, 4, v2
	v_cmp_eq_u32_e64 s[16:17], 0, v3
	v_cndmask_b32_e32 v1, v229, v1, vcc
	v_lshlrev_b32_e32 v244, 2, v1
	v_xor_b32_e32 v1, 1, v229
	v_cmp_lt_i32_e32 vcc, v1, v4
	v_lshlrev_b32_e32 v4, 7, v6
	v_lshl_add_u64 v[124:125], s[24:25], 0, v[4:5]
	v_cndmask_b32_e32 v1, v229, v1, vcc
	v_lshlrev_b32_e32 v245, 2, v1
	v_lshl_add_u64 v[126:127], s[22:23], 0, v[4:5]
	v_lshl_add_u64 v[128:129], s[2:3], 0, v[4:5]
	s_mov_b64 s[22:23], 0
	v_lshlrev_b32_e32 v130, 2, v2
	v_lshlrev_b32_e32 v132, 2, v0
	s_branch .LBB0_328

.Lg_tail_check:
	s_cmp_eq_u32 s54, 0
	s_cbranch_scc1 .LBB0_344
	s_mov_b32 s54, 0
	s_mov_b64 exec, s[0:1]
	s_mov_b32 s58, 0
	s_movk_i32 s61, 0xe00
	v_readlane_b32 s2, v249, 0
	s_lshl_b32 s2, s2, 2
	s_add_u32 s2, s2, s60
	v_mov_b32_e32 v116, s2
	s_mov_b64 s[22:23], 0
	s_branch .LBB0_328
